# prep gate-vector loads issued at stage start (hidden behind the conv) instead of in the gate block
# baseline (speedup 1.0000x reference)
.LBB0_348:
	s_mul_hi_i32 s28, s54, 0x2aaaaaab
	s_lshr_b32 s29, s28, 31
	s_add_i32 s22, s28, s29
	s_ashr_i32 s2, s22, 31
	s_lshr_b32 s2, s2, 27
	s_add_i32 s2, s22, s2
	v_mov_b32_e32 v80, v225
	s_and_b32 s2, s2, 0x3ffffe0
	s_sub_i32 s2, s22, s2
	v_lshlrev_b32_e32 v0, 3, v80
	s_lshl_b32 s23, s2, 6
	v_and_b32_e32 v14, 56, v0
	s_mul_i32 s2, s22, 0x180
	v_ashrrev_i32_e32 v58, 3, v80
	v_subrev_u32_e32 v0, s2, v14
	v_add_u32_e32 v0, s53, v0
	v_add_u32_e32 v12, s23, v58
	v_add_u32_e32 v2, -1, v12
	v_ashrrev_i32_e32 v1, 31, v0
	s_movk_i32 s2, 0x800
	v_mov_b32_e32 v10, 0
	v_lshl_add_u64 v[0:1], v[0:1], 2, s[0:1]
	s_mov_b64 s[4:5], 0x1200
	v_lshl_add_u64 v[218:219], v[0:1], 0, s[4:5]
	s_mov_b64 s[4:5], 0x2400
	v_lshl_add_u64 v[244:245], v[0:1], 0, s[4:5]
	global_load_dwordx4 v[154:157], v[218:219], off
	global_load_dwordx4 v[158:161], v[218:219], off offset:16
	global_load_dwordx4 v[162:165], v[244:245], off
	global_load_dwordx4 v[166:169], v[244:245], off offset:16
	global_load_dwordx4 v[170:173], v[0:1], off offset:1536
	global_load_dwordx4 v[174:177], v[0:1], off offset:1552
	global_load_dwordx4 v[178:181], v[218:219], off offset:1536
	global_load_dwordx4 v[182:185], v[218:219], off offset:1552
	global_load_dwordx4 v[186:189], v[244:245], off offset:1536
	global_load_dwordx4 v[190:193], v[244:245], off offset:1552
	global_load_dwordx4 v[194:197], v[0:1], off offset:3072
	global_load_dwordx4 v[198:201], v[0:1], off offset:3088
	global_load_dwordx4 v[202:205], v[218:219], off offset:3072
	global_load_dwordx4 v[206:209], v[218:219], off offset:3088
	global_load_dwordx4 v[210:213], v[244:245], off offset:3072
	global_load_dwordx4 v[226:229], v[244:245], off offset:3088
	s_ashr_i32 s6, s28, 5
	s_add_i32 s6, s6, s29
	s_ashr_i32 s7, s6, 31
	s_lshl_b64 s[6:7], s[6:7], 11
	s_ashr_i32 s8, s23, 31
	s_add_u32 s6, s23, s6
	s_addc_u32 s7, s8, s7
	s_mul_i32 s8, s22, -6
	s_add_i32 s8, s54, s8
	s_ashr_i32 s9, s8, 31
	v_readlane_b32 s10, v252, 0
	v_readlane_b32 s11, v252, 1
	s_movk_i32 s12, 0xa00
	v_and_b32_e32 v70, 63, v80
	v_mov_b32_e32 v71, 0
	v_lshl_add_u64 v[70:71], s[6:7], 0, v[70:71]
	v_mov_b64_e32 v[72:73], s[10:11]
	v_lshrrev_b32_e32 v74, 6, v80
	v_mad_u64_u32 v[72:73], s[10:11], v70, s12, v[72:73]
	v_and_b32_e32 v74, 1, v74
	v_mad_i32_i24 v73, v71, s12, v73
	v_lshl_add_u64 v[70:71], s[8:9], 1, v[72:73]
	v_mul_u32_u24_e32 v72, 12, v74
	v_mov_b32_e32 v73, 0
	s_lshl_b32 s8, s8, 2
	v_lshl_add_u64 v[70:71], v[70:71], 0, v[72:73]
	v_mov_b32_e32 v75, s8
	v_mad_u32_u24 v75, v74, 24, v75
	global_load_ushort v66, v[70:71], off offset:2304
	global_load_ushort v67, v[70:71], off offset:2328
	global_load_dword v68, v75, s[48:49]
	global_load_dword v69, v75, s[50:51]
	v_cmp_gt_u32_e64 s[42:43], s2, v2
	v_mov_b32_e32 v11, 0
	v_mov_b32_e32 v2, 0
	v_mov_b32_e32 v3, 0
	v_mov_b32_e32 v4, 0
	v_mov_b32_e32 v5, v10
	v_mov_b32_e32 v6, v10
	v_mov_b32_e32 v7, v10
	v_mov_b32_e32 v8, 0
	v_mov_b32_e32 v9, 0
	s_and_saveexec_b64 s[2:3], s[42:43]
	s_cbranch_execz .LBB0_350
	global_load_dwordx4 v[6:9], v[0:1], off offset:16
	global_load_dwordx4 v[2:5], v[0:1], off
	s_waitcnt vmcnt(10)
	v_lshlrev_b32_e32 v10, 16, v16
	v_and_b32_e32 v11, 0xffff0000, v16
	s_waitcnt vmcnt(0)
	v_pk_fma_f32 v[2:3], v[2:3], v[10:11], 0 op_sel_hi:[1,1,0]
	v_lshlrev_b32_e32 v10, 16, v18
	v_and_b32_e32 v11, 0xffff0000, v18
	v_pk_fma_f32 v[6:7], v[6:7], v[10:11], 0 op_sel_hi:[1,1,0]
	v_lshlrev_b32_e32 v10, 16, v17
	v_and_b32_e32 v11, 0xffff0000, v17
	v_pk_fma_f32 v[4:5], v[4:5], v[10:11], 0 op_sel_hi:[1,1,0]
	v_lshlrev_b32_e32 v10, 16, v19
	v_and_b32_e32 v11, 0xffff0000, v19
	v_pk_fma_f32 v[10:11], v[8:9], v[10:11], 0 op_sel_hi:[1,1,0]
	s_nop 0
	v_mov_b32_e32 v8, v10
	v_mov_b32_e32 v9, v11

.LBB0_362:
	s_or_b64 exec, exec, s[2:3]
	v_mul_f32_e32 v0, 0xbfb8aa3b, v5
	v_exp_f32_e32 v1, v0
	v_mul_f32_e32 v0, 0xbfb8aa3b, v8
	v_exp_f32_e32 v10, v0
	v_mul_f32_e32 v0, 0xbfb8aa3b, v9
	v_exp_f32_e32 v11, v0
	v_mul_f32_e32 v0, 0xbfb8aa3b, v6
	v_exp_f32_e32 v14, v0
	v_mul_f32_e32 v0, 0xbfb8aa3b, v7
	v_pk_add_f32 v[10:11], v[10:11], 1.0 op_sel_hi:[1,0]
	v_exp_f32_e32 v15, v0
	v_div_scale_f32 v13, s[2:3], v11, v11, v9
	v_rcp_f32_e32 v54, v13
	v_mul_f32_e32 v0, 0xbfb8aa3b, v2
	v_exp_f32_e32 v52, v0
	v_mul_f32_e32 v0, 0xbfb8aa3b, v3
	v_fma_f32 v55, -v13, v54, 1.0
	v_fmac_f32_e32 v54, v55, v54
	v_div_scale_f32 v55, vcc, v9, v11, v9
	v_mul_f32_e32 v56, v55, v54
	v_fma_f32 v57, -v13, v56, v55
	v_fmac_f32_e32 v56, v57, v54
	v_fma_f32 v13, -v13, v56, v55
	v_div_fmas_f32 v13, v13, v54, v56
	v_div_fixup_f32 v9, v13, v11, v9
	v_div_scale_f32 v11, s[2:3], v10, v10, v8
	v_rcp_f32_e32 v13, v11
	v_exp_f32_e32 v53, v0
	v_mul_f32_e32 v0, 0xbfb8aa3b, v4
	v_exp_f32_e32 v0, v0
	v_fma_f32 v54, -v11, v13, 1.0
	v_fmac_f32_e32 v13, v54, v13
	v_div_scale_f32 v54, vcc, v8, v10, v8
	v_mul_f32_e32 v55, v54, v13
	v_fma_f32 v56, -v11, v55, v54
	v_fmac_f32_e32 v55, v56, v13
	v_fma_f32 v11, -v11, v55, v54
	v_div_fmas_f32 v11, v11, v13, v55
	v_div_fixup_f32 v8, v11, v10, v8
	v_add_u32_e32 v10, 0x8900, v12
	ds_write2_b32 v10, v8, v9 offset1:1
	v_pk_add_f32 v[8:9], v[14:15], 1.0 op_sel_hi:[1,0]
	v_pk_add_f32 v[0:1], v[0:1], 1.0 op_sel_hi:[1,0]
	v_div_scale_f32 v10, s[2:3], v9, v9, v7
	v_rcp_f32_e32 v11, v10
	s_nop 0
	v_fma_f32 v13, -v10, v11, 1.0
	v_fmac_f32_e32 v11, v13, v11
	v_div_scale_f32 v13, vcc, v7, v9, v7
	v_mul_f32_e32 v14, v13, v11
	v_fma_f32 v15, -v10, v14, v13
	v_fmac_f32_e32 v14, v15, v11
	v_fma_f32 v10, -v10, v14, v13
	v_div_fmas_f32 v10, v10, v11, v14
	v_div_fixup_f32 v7, v10, v9, v7
	v_div_scale_f32 v9, s[2:3], v8, v8, v6
	v_rcp_f32_e32 v10, v9
	s_nop 0
	v_fma_f32 v11, -v9, v10, 1.0
	v_fmac_f32_e32 v10, v11, v10
	v_div_scale_f32 v11, vcc, v6, v8, v6
	v_mul_f32_e32 v13, v11, v10
	v_fma_f32 v14, -v9, v13, v11
	v_fmac_f32_e32 v13, v14, v10
	v_fma_f32 v9, -v9, v13, v11
	v_div_fmas_f32 v9, v9, v10, v13
	v_div_fixup_f32 v6, v9, v8, v6
	v_add_u32_e32 v8, 0x8908, v12
	ds_write2_b32 v8, v6, v7 offset1:1
	v_pk_add_f32 v[6:7], v[52:53], 1.0 op_sel_hi:[1,0]
	s_nop 0
	v_div_scale_f32 v8, s[2:3], v7, v7, v3
	v_rcp_f32_e32 v9, v8
	s_nop 0
	v_fma_f32 v10, -v8, v9, 1.0
	v_fmac_f32_e32 v9, v10, v9
	v_div_scale_f32 v10, vcc, v3, v7, v3
	v_mul_f32_e32 v11, v10, v9
	v_fma_f32 v13, -v8, v11, v10
	v_fmac_f32_e32 v11, v13, v9
	v_fma_f32 v8, -v8, v11, v10
	v_div_fmas_f32 v8, v8, v9, v11
	v_div_fixup_f32 v3, v8, v7, v3
	v_div_scale_f32 v7, s[2:3], v6, v6, v2
	v_rcp_f32_e32 v8, v7
	s_nop 0
	v_fma_f32 v9, -v7, v8, 1.0
	v_fmac_f32_e32 v8, v9, v8
	v_div_scale_f32 v9, vcc, v2, v6, v2
	v_mul_f32_e32 v10, v9, v8
	v_fma_f32 v11, -v7, v10, v9
	v_fmac_f32_e32 v10, v11, v8
	v_fma_f32 v7, -v7, v10, v9
	v_div_fmas_f32 v7, v7, v8, v10
	v_div_fixup_f32 v2, v7, v6, v2
	v_add_u32_e32 v6, 0x8910, v12
	ds_write2_b32 v6, v2, v3 offset1:1
	v_div_scale_f32 v2, s[2:3], v1, v1, v5
	v_rcp_f32_e32 v3, v2
	s_nop 0
	v_fma_f32 v6, -v2, v3, 1.0
	v_fmac_f32_e32 v3, v6, v3
	v_div_scale_f32 v6, vcc, v5, v1, v5
	v_mul_f32_e32 v7, v6, v3
	v_fma_f32 v8, -v2, v7, v6
	v_fmac_f32_e32 v7, v8, v3
	v_fma_f32 v2, -v2, v7, v6
	v_div_fmas_f32 v2, v2, v3, v7
	v_div_fixup_f32 v1, v2, v1, v5
	v_div_scale_f32 v2, s[2:3], v0, v0, v4
	v_rcp_f32_e32 v3, v2
	s_nop 0
	v_fma_f32 v5, -v2, v3, 1.0
	v_fmac_f32_e32 v3, v5, v3
	v_div_scale_f32 v5, vcc, v4, v0, v4
	v_mul_f32_e32 v6, v5, v3
	v_fma_f32 v7, -v2, v6, v5
	v_fmac_f32_e32 v6, v7, v3
	v_fma_f32 v2, -v2, v6, v5
	v_div_fmas_f32 v2, v2, v3, v6
	v_div_fixup_f32 v0, v2, v0, v4
	v_add_u32_e32 v2, 0x8918, v12
	v_cmp_gt_i32_e32 vcc, 0x80, v80
	ds_write2_b32 v2, v0, v1 offset1:1
	s_and_saveexec_b64 s[2:3], vcc
	s_cbranch_execz .LBB0_364
	s_mov_b32 s9, 0xbfb8aa3b
	s_mov_b32 s10, 0x3f2aaaab
	s_mov_b32 s11, 0x3f317218
	s_mov_b32 s8, 0x7f800000
	s_mov_b32 s12, 0x33800000
	s_waitcnt vmcnt(0)
	v_mov_b32_e32 v2, v66
	v_lshlrev_b32_e32 v2, 16, v2
	v_mul_f32_e32 v2, 0xbfb8aa3b, v2
	v_exp_f32_e32 v2, v2
	s_nop 0
	v_add_f32_e32 v2, 1.0, v2
	v_div_scale_f32 v3, s[4:5], v2, v2, 1.0
	v_rcp_f32_e32 v4, v3
	s_nop 0
	v_fma_f32 v5, -v3, v4, 1.0
	v_fmac_f32_e32 v4, v5, v4
	v_div_scale_f32 v5, vcc, 1.0, v2, 1.0
	v_mul_f32_e32 v6, v5, v4
	v_fma_f32 v7, -v3, v6, v5
	v_fmac_f32_e32 v6, v7, v4
	v_fma_f32 v3, -v3, v6, v5
	v_div_fmas_f32 v3, v3, v4, v6
	v_div_fixup_f32 v3, v3, v2, 1.0
	v_lshl_add_u32 v2, v80, 2, 0
	v_add_u32_e32 v2, 0x21a00, v2
	ds_write_b32 v2, v3 offset:512
	v_mov_b32_e32 v4, v67
	v_mov_b32_e32 v3, v68
	v_mov_b32_e32 v5, v69
	v_lshlrev_b32_e32 v4, 16, v4
	v_mul_f32_e32 v3, 0x3fb8aa3b, v3
	v_add_f32_e32 v4, v5, v4
	v_max_f32_e32 v6, 0, v4
	v_mul_f32_e64 v4, |v4|, s9
	v_exp_f32_e32 v7, v4
	v_exp_f32_e32 v3, v3
	v_add_f32_e32 v8, 1.0, v7
	v_add_f32_e32 v4, -1.0, v8
	v_sub_f32_e32 v5, v4, v8
	v_add_f32_e32 v5, 1.0, v5
	v_sub_f32_e32 v4, v7, v4
	v_add_f32_e32 v9, v4, v5
	v_frexp_mant_f32_e32 v4, v8
	v_cmp_gt_f32_e32 vcc, s10, v4
	v_cvt_f64_f32_e32 v[4:5], v8
	v_frexp_exp_i32_f64_e32 v4, v[4:5]
	v_subbrev_co_u32_e32 v4, vcc, 0, v4, vcc
	v_sub_u32_e32 v5, 0, v4
	v_ldexp_f32 v8, v8, v5
	v_ldexp_f32 v5, v9, v5
	v_add_f32_e32 v9, -1.0, v8
	v_add_f32_e32 v10, 1.0, v9
	v_sub_f32_e32 v10, v8, v10
	v_add_f32_e32 v10, v5, v10
	v_add_f32_e32 v11, v9, v10
	v_sub_f32_e32 v9, v11, v9
	v_sub_f32_e32 v9, v10, v9
	v_add_f32_e32 v10, 1.0, v8
	v_add_f32_e32 v12, -1.0, v10
	v_sub_f32_e32 v8, v8, v12
	v_add_f32_e32 v5, v5, v8
	v_add_f32_e32 v8, v10, v5
	v_sub_f32_e32 v10, v8, v10
	v_sub_f32_e32 v5, v5, v10
	v_rcp_f32_e32 v10, v8
	v_cvt_f32_i32_e32 v4, v4
	v_cmp_neq_f32_e32 vcc, s8, v7
	v_mul_f32_e32 v12, v11, v10
	v_mul_f32_e32 v13, v8, v12
	v_fma_f32 v14, v12, v8, -v13
	v_fmac_f32_e32 v14, v12, v5
	v_add_f32_e32 v15, v13, v14
	v_sub_f32_e32 v52, v11, v15
	v_sub_f32_e32 v11, v11, v52
	v_sub_f32_e32 v13, v15, v13
	v_sub_f32_e32 v11, v11, v15
	v_add_f32_e32 v9, v9, v11
	v_sub_f32_e32 v11, v13, v14
	v_add_f32_e32 v9, v11, v9
	v_add_f32_e32 v11, v52, v9
	v_mul_f32_e32 v13, v10, v11
	v_mul_f32_e32 v14, v8, v13
	v_fma_f32 v8, v13, v8, -v14
	v_fmac_f32_e32 v8, v13, v5
	v_sub_f32_e32 v5, v52, v11
	v_add_f32_e32 v5, v9, v5
	v_add_f32_e32 v9, v14, v8
	v_sub_f32_e32 v15, v11, v9
	v_sub_f32_e32 v11, v11, v15
	v_sub_f32_e32 v14, v9, v14
	v_sub_f32_e32 v9, v11, v9
	v_add_f32_e32 v5, v5, v9
	v_sub_f32_e32 v8, v14, v8
	v_add_f32_e32 v5, v8, v5
	v_add_f32_e32 v8, v12, v13
	v_add_f32_e32 v5, v15, v5
	v_sub_f32_e32 v9, v8, v12
	v_mul_f32_e32 v5, v10, v5
	v_sub_f32_e32 v9, v13, v9
	v_add_f32_e32 v5, v9, v5
	v_mul_f32_e32 v12, 0x3f317218, v4
	v_add_f32_e32 v9, v8, v5
	v_fma_f32 v13, v4, s11, -v12
	v_mul_f32_e32 v10, v9, v9
	v_fmac_f32_e32 v13, 0xb102e308, v4
	v_sub_f32_e32 v4, v9, v8
	v_fmamk_f32 v11, v10, 0x3e9b6dac, v237
	v_sub_f32_e32 v4, v5, v4
	v_add_f32_e32 v5, v12, v13
	v_fmaak_f32 v11, v10, v11, 0x3f2aaada
	v_sub_f32_e32 v8, v5, v12
	v_ldexp_f32 v12, v9, 1
	v_mul_f32_e32 v9, v9, v10
	v_mul_f32_e32 v9, v9, v11
	v_add_f32_e32 v10, v12, v9
	v_sub_f32_e32 v11, v10, v12
	v_ldexp_f32 v4, v4, 1
	v_sub_f32_e32 v9, v9, v11
	v_add_f32_e32 v4, v4, v9
	v_add_f32_e32 v9, v10, v4
	v_sub_f32_e32 v10, v9, v10
	v_sub_f32_e32 v4, v4, v10
	v_add_f32_e32 v10, v5, v9
	v_sub_f32_e32 v11, v10, v5
	v_sub_f32_e32 v12, v10, v11
	v_sub_f32_e32 v8, v13, v8
	v_sub_f32_e32 v5, v5, v12
	v_sub_f32_e32 v9, v9, v11
	v_add_f32_e32 v5, v9, v5
	v_add_f32_e32 v9, v8, v4
	v_sub_f32_e32 v11, v9, v8
	v_sub_f32_e32 v12, v9, v11
	v_sub_f32_e32 v8, v8, v12
	v_sub_f32_e32 v4, v4, v11
	v_add_f32_e32 v5, v9, v5
	v_add_f32_e32 v4, v4, v8
	v_add_f32_e32 v8, v10, v5
	v_sub_f32_e32 v9, v8, v10
	v_sub_f32_e32 v5, v5, v9
	v_add_f32_e32 v4, v4, v5
	v_add_f32_e32 v4, v8, v4
	v_cndmask_b32_e32 v4, v239, v4, vcc
	v_cmp_ngt_f32_e32 vcc, -1.0, v7
	s_nop 1
	v_cndmask_b32_e32 v4, v238, v4, vcc
	v_cmp_neq_f32_e32 vcc, -1.0, v7
	s_nop 1
	v_cndmask_b32_e32 v4, v243, v4, vcc
	v_cmp_lt_f32_e64 vcc, |v7|, s12
	s_nop 1
	v_cndmask_b32_e32 v4, v4, v7, vcc
	v_add_f32_e32 v4, v6, v4
	v_mul_f32_e64 v3, v4, -v3
	ds_write_b32 v2, v3
